# attention K/V staging loads: scalar base + per-lane 32-bit offsets carried across tiles (no per-tile 64-bit address arithmetic, no waits before re-issuing)
# speedup vs baseline: 1.0010x; 1.0010x over previous
; #define LSTOREX(P, st_) { LST1(st_, 0, P##k0) LST1(st_, 1, P##k1) LST1(st_, 2, P##k2) \
;                           *(uint4*)(smem + (st_) + KSZ + vdv * VROW + vcc * 16) = P##v0; *(uint4*)(smem + (st_) + KSZ + (vdv + 32) * VROW + vcc * 16) = P##v1; }
; __device__ __forceinline__ void attn_unit(const Params& p, int b, int h, int q0, int nkeys, char* smem) {
;     ...
;     uint4 ak0, ak1, ak2, av0, av1, bk0, bk1, bk2, bv0, bv1;
;     const int vdv = tid >> 3, vcc = tid & 7;
;     ...
;     const int nt = nkeys >> 6;
;     __syncthreads();
;     GLOADX(a, 0)
;     LSTOREX(a, 0)
;     GLOADX(a, 64)
;     __syncthreads();
;     ...
;     for (int kt2 = 0; kt2 < nt; kt2 += 2) {
;         ATT_BODY(kt2, b, a)
;         ATT_BODY(kt2 + 1, a, b)
;     }
.LBB0_458:
	s_lshl_b32 s0, s31, 3
	s_add_i32 s46, s34, s0
	v_mov_b32_e32 v64, v109
	s_mul_i32 s44, s46, 0xcc000
	v_readlane_b32 s0, v251, 56
	s_mul_hi_i32 s42, s46, 0xcc000
	v_and_b32_e32 v72, 15, v64
	v_bfe_u32 v28, v64, 4, 2
	v_readlane_b32 s1, v251, 57
	s_add_u32 s0, s0, s44
	v_ashrrev_i32_e32 v0, 1, v64
	s_addc_u32 s1, s1, s42
	v_readlane_b32 s4, v251, 58
	v_and_b32_e32 v114, 0xffffffe0, v0
	v_add_u32_e32 v111, s43, v72
	v_lshlrev_b32_e32 v104, 4, v28
	s_add_u32 s44, s4, s44
	v_add_u32_e32 v12, v111, v114
	s_waitcnt vmcnt(0)
	v_lshl_add_u64 v[8:9], s[0:1], 0, v[104:105]
	s_movk_i32 s4, 0xc0
	v_readlane_b32 s5, v251, 59
	v_mad_i64_i32 v[10:11], s[0:1], v12, s4, v[8:9]
	v_add_u32_e32 v12, 16, v12
	v_ashrrev_i32_e32 v65, 31, v64
	s_addc_u32 s45, s5, s42
	v_mad_i64_i32 v[20:21], s[0:1], v12, s4, v[8:9]
	v_lshlrev_b64 v[66:67], 4, v[64:65]
	s_mul_i32 s47, s46, 0x88000
	v_readlane_b32 s0, v251, 60
	v_lshl_add_u64 v[24:25], s[44:45], 0, v[66:67]
	s_movk_i32 s4, 0x2000
	s_mul_hi_i32 s42, s46, 0x88000
	s_add_u32 s0, s0, s47
	v_readlane_b32 s1, v251, 61
	v_add_co_u32_e32 v26, vcc, s4, v24
	global_load_dwordx4 v[0:3], v[10:11], off
	global_load_dwordx4 v[4:7], v[10:11], off offset:64
	s_nop 0
	global_load_dwordx4 v[8:11], v[10:11], off offset:128
	s_nop 0
	global_load_dwordx4 v[12:15], v[20:21], off
	global_load_dwordx4 v[16:19], v[20:21], off offset:64
	s_nop 0
	global_load_dwordx4 v[20:23], v[20:21], off offset:128
	s_barrier
	global_load_dwordx4 v[44:47], v[24:25], off
	s_addc_u32 s1, s1, s42
	v_addc_co_u32_e32 v27, vcc, 0, v25, vcc
	v_ashrrev_i32_e32 v65, 3, v64
	global_load_dwordx4 v[48:51], v[26:27], off offset:-4096
	global_load_dwordx4 v[52:55], v[26:27], off
	v_mov_b64_e32 v[26:27], s[0:1]
	s_movk_i32 s4, 0x2200
	v_lshlrev_b32_e32 v29, 4, v64
	v_mad_i64_i32 v[26:27], s[0:1], v65, s4, v[26:27]
	v_and_b32_e32 v68, 0x70, v29
	v_mov_b32_e32 v69, v105
	v_lshl_add_u64 v[32:33], v[26:27], 0, v[68:69]
	s_mov_b32 s0, 0x44000
	v_add_co_u32_e32 v40, vcc, s0, v32
	s_movk_i32 s0, 0x4000
	s_nop 0
	v_addc_co_u32_e32 v41, vcc, 0, v33, vcc
	v_lshlrev_b32_e32 v116, 3, v28
	v_add_co_u32_e32 v28, vcc, s0, v24
	s_movk_i32 s0, 0x5000
	s_nop 0
	v_addc_co_u32_e32 v29, vcc, 0, v25, vcc
	v_add_co_u32_e32 v36, vcc, s0, v24
	global_load_dwordx4 v[56:59], v[32:33], off
	global_load_dwordx4 v[60:63], v[40:41], off
	v_addc_co_u32_e32 v37, vcc, 0, v25, vcc
	global_load_dwordx4 v[24:27], v[28:29], off offset:-4096
	s_nop 0
	global_load_dwordx4 v[28:31], v[28:29], off
	s_nop 0
	global_load_dwordx4 v[32:35], v[32:33], off offset:128
	s_nop 0
	global_load_dwordx4 v[36:39], v[36:37], off
	s_nop 0
	global_load_dwordx4 v[40:43], v[40:41], off offset:128
	s_mov_b32 s5, 0x2aaaaaab
	v_mul_hi_i32 v69, v64, s5
	v_lshrrev_b32_e32 v74, 31, v69
	v_ashrrev_i32_e32 v69, 1, v69
	v_mad_i64_i32 v[70:71], s[0:1], v65, s4, 0
	v_add_u32_e32 v69, v69, v74
	v_mul_lo_u32 v76, v69, -12
	s_movk_i32 s0, 0xd0
	v_add_u32_e32 v73, 0x100, v64
	v_mul_lo_u32 v69, v69, s0
	v_add_lshl_u32 v76, v76, v64, 4
	v_mul_hi_i32 v75, v73, s5
	v_add_u32_e32 v115, v69, v76
	v_lshrrev_b32_e32 v74, 31, v75
	v_mov_b32_e32 v92, 0
	s_mov_b32 s42, 3
	v_mov_b32_e32 v93, v92
	v_mov_b32_e32 v94, v92
	v_mov_b32_e32 v95, v92
	v_mov_b32_e32 v84, v92
	v_mov_b32_e32 v85, v92
	v_mov_b32_e32 v86, v92
	v_mov_b32_e32 v87, v92
	v_mov_b32_e32 v88, v92
	v_mov_b32_e32 v89, v92
	v_mov_b32_e32 v90, v92
	v_mov_b32_e32 v91, v92
	v_mov_b32_e32 v76, v92
	v_mov_b32_e32 v77, v92
	v_mov_b32_e32 v78, v92
	v_mov_b32_e32 v79, v92
	v_mov_b32_e32 v80, v92
	v_mov_b32_e32 v81, v92
	v_mov_b32_e32 v82, v92
	v_mov_b32_e32 v83, v92
	v_mov_b32_e32 v69, v92
	v_mov_b32_e32 v118, v92
	v_mov_b32_e32 v119, v92
	s_waitcnt vmcnt(9)
	ds_write_b128 v115, v[44:47]
	v_ashrrev_i32_e32 v44, 1, v75
	v_add_u32_e32 v44, v44, v74
	v_mul_lo_u32 v45, v44, -12
	v_mul_lo_u32 v44, v44, s0
	v_add_lshl_u32 v45, v45, v73, 4
	v_add_u32_e32 v117, v44, v45
	v_add_u32_e32 v44, 0x200, v64
	v_mul_hi_i32 v45, v44, s5
	v_lshrrev_b32_e32 v46, 31, v45
	v_ashrrev_i32_e32 v45, 1, v45
	v_add_u32_e32 v45, v45, v46
	v_mul_lo_u32 v46, v45, -12
	v_mul_lo_u32 v45, v45, s0
	v_add_lshl_u32 v44, v46, v44, 4
	s_movk_i32 s0, 0x90
	v_add_u32_e32 v217, v45, v44
	v_mul_lo_u32 v44, v65, s0
	v_add_u32_e32 v218, v44, v68
	v_sub_u32_e32 v44, v104, v116
	v_mul_u32_u24_e32 v45, 0xd0, v72
	v_mul_u32_u24_e32 v46, 0x90, v72
	v_mad_i64_i32 v[120:121], s[0:1], s46, v200, v[70:71]
	v_or_b32_e32 v120, v120, v68
	v_mad_i64_i32 v[122:123], s[0:1], s46, v203, v[66:67]
	v_add_u32_e32 v104, v104, v45
	v_add_u32_e32 v219, v44, v46
	v_mov_b32_e32 v68, v92
	v_mov_b32_e32 v70, v92
	v_mov_b32_e32 v71, v92
	v_mov_b32_e32 v72, v92
	v_mov_b32_e32 v73, v92
	v_mov_b32_e32 v74, v92
	v_mov_b32_e32 v75, v92
	v_mov_b32_e32 v64, v92
	v_mov_b32_e32 v65, v92
	v_mov_b32_e32 v66, v92
	v_mov_b32_e32 v67, v92
	s_waitcnt vmcnt(8)
	ds_write_b128 v117, v[48:51]
	s_waitcnt vmcnt(7)
	ds_write_b128 v217, v[52:55]
	s_waitcnt vmcnt(6)
	ds_write_b128 v218, v[56:59] offset:13312
	s_waitcnt vmcnt(5)
	ds_write_b128 v218, v[60:63] offset:17920
	s_waitcnt lgkmcnt(0)
	s_barrier
	v_add_u32_e32 v178, 0x3400, v219
	v_add_u32_e32 v179, 0x3d00, v219
	v_add_u32_e32 v191, 0x4600, v219
	v_add_u32_e32 v208, 0x4f00, v219
	v_add_u32_e32 v209, 0x8c00, v219
	v_add_u32_e32 v210, 0x9500, v219
	v_add_u32_e32 v211, 0x9e00, v219
	v_add_u32_e32 v212, 0xa700, v219
	v_mov_b32_e32 v176, 0
	v_mov_b32_e32 v177, 0
	s_add_u32 s98, s26, 0x185a9000
	s_addc_u32 s99, s27, 0
	s_add_u32 s100, s26, 0x1b8a3000
	s_addc_u32 s101, s27, 0
	v_add_u32_e32 v178, 0x1000, v122
	v_add_u32_e32 v179, 0x3000, v122
	v_add_u32_e32 v191, 0x5000, v122
	v_add_u32_e32 v208, 0x44000, v120
	s_branch .LBB0_460
.LBB0_459:
	v_add_u32_e32 v178, 0x6000, v178
	v_add_u32_e32 v179, 0x6000, v179
	v_add_u32_e32 v191, 0x6000, v191
	v_add_u32_e32 v208, 0x100, v208
	s_mov_b64 s[0:1], 0x100
	v_lshl_add_u64 v[120:121], v[120:121], 0, s[0:1]
	s_add_i32 s42, s42, 2
	s_mov_b64 s[0:1], 0x6000
	s_cmp_lt_u32 s43, s35
	v_lshl_add_u64 v[122:123], v[122:123], 0, s[0:1]
	s_waitcnt lgkmcnt(0)
	s_barrier
	s_cbranch_scc0 .LBB0_447
.LBB0_460:
	s_add_i32 s43, s42, -1
	s_mov_b64 s[4:5], s[20:21]
	s_cmp_lt_u32 s43, s35
	s_mov_b64 s[10:11], s[26:27]
	s_cselect_b64 s[0:1], -1, 0
	s_cmp_ge_u32 s43, s35
	s_mov_b64 s[6:7], s[22:23]
	s_mov_b64 s[8:9], s[24:25]
	s_cbranch_scc1 .LBB0_462
	global_load_dwordx4 v[44:47], v178, s[98:99] offset:-4096
	global_load_dwordx4 v[48:51], v178, s[98:99]
	global_load_dwordx4 v[52:55], v179, s[98:99] offset:-4096
	global_load_dwordx4 v[56:59], v120, s[100:101] offset:256
	global_load_dwordx4 v[60:63], v208, s[100:101] offset:256

.LBB0_464:
	s_cmp_ge_u32 s42, s35
	s_waitcnt lgkmcnt(0)
	s_barrier
	s_cbranch_scc1 .LBB0_466
	global_load_dwordx4 v[24:27], v179, s[98:99]
	global_load_dwordx4 v[28:31], v191, s[98:99] offset:-4096
	global_load_dwordx4 v[36:39], v191, s[98:99]
	global_load_dwordx4 v[32:35], v120, s[100:101] offset:384
	global_load_dwordx4 v[40:43], v208, s[100:101] offset:384
